# residual-stream stores deferred until after the second row-exchange (slot-store ack no longer waits for the store burst)
# speedup vs baseline: 1.0092x; 1.0053x over previous
; __device__ __forceinline__ void row_exchange(const f32x4 (&v)[2][2][4][2], const Unit& u, int wr, int wc, int fr, int fq, LAS unsigned char* lds, int wid, int lane, float* slots, unsigned* cnt) {
;     ...
;     asm volatile("s_waitcnt lgkmcnt(0)" ::: "memory"); __builtin_amdgcn_s_barrier(); asm volatile("" ::: "memory");
;     const int row = wid * 32 + (lane & 31);
;     if (lane < 32) {
;         const float tot = (P[row * 4 + 0] + P[row * 4 + 1]) + (P[row * 4 + 2] + P[row * 4 + 3]);
;         __hip_atomic_store((unsigned*)slots + ((size_t)(u.pm * BM + row) * 4 + u.pn), __float_as_uint(tot), __ATOMIC_RELAXED, __HIP_MEMORY_SCOPE_AGENT);
;     }
;     asm volatile("s_waitcnt vmcnt(0)" ::: "memory");
;     if (lane == 0) __hip_atomic_fetch_add(cnt + 64 * u.pm, 1u, __ATOMIC_RELAXED, __HIP_MEMORY_SCOPE_AGENT);
;     __device__ __forceinline__ void fused(f32x4 (&acc)[2][2][4][2], const Unit& u, int wr, int wc, int fr, int fq, LAS unsigned char* lds, int wid, int lane) const {
;     ...
; #pragma unroll
;                 for (int m = 0; m < 4; ++m) { const int r = ai * HALF + wr * 64 + m * 16 + fr; const float r1 = rsqrtf(S[r] * (1.0f / D) + EPS) * wgt; const size_t off = (size_t)(u.pm * BM + r) * D + col0;
; #pragma unroll
;                     for (int bj = 0; bj < 2; ++bj)
; #pragma unroll
;                         for (int n = 0; n < 2; ++n) { const f32x4 xv = *(const f32x4*)(xin + off + bj * HALF + n * 16); const f32x4 xn = xv + (cw[bj][n] * r1) * acc[ai][bj][m][n];
;                             acc[ai][bj][m][n] = xn; *(f32x4*)(xout + off + bj * HALF + n * 16) = xn; }
;                     asm volatile("" : "+v"(acc[ai][0][m][0]), "+v"(acc[ai][0][m][1]), "+v"(acc[ai][1][m][0]), "+v"(acc[ai][1][m][1]));
;                     asm volatile("" ::: "memory"); }
.LBB0_1116:
	s_or_b64 exec, exec, s[48:49]
	v_readlane_b32 s18, v253, 36
	s_lshl_b32 s0, s15, 5
	s_lshl_b32 s1, s86, 8
	s_mul_i32 s15, s18, 45
	s_or_b32 s0, s1, s0
	v_lshrrev_b32_e32 v128, 2, v138
	s_add_i32 s15, s12, s15
	v_and_or_b32 v154, v128, 12, s0
	s_ashr_i32 s0, s33, 4
	s_lshl_b32 s15, s15, 12
	s_mul_hi_i32 s1, s0, 0x2400
	s_mulk_i32 s0, 0x2400
	s_add_u32 s15, s94, s15
	s_addc_u32 s18, s95, 0
	s_lshl_b64 s[94:95], s[0:1], 2
	s_add_u32 s0, s15, s94
	v_ashrrev_i32_e32 v155, 31, v154
	s_addc_u32 s1, s18, s95
	v_lshlrev_b64 v[128:129], 2, v[154:155]
	v_lshl_add_u64 v[132:133], s[0:1], 0, v[128:129]
	s_mov_b64 s[0:1], 0xa300000
	v_lshl_add_u64 v[162:163], v[132:133], 0, s[0:1]
	v_readlane_b32 s0, v253, 43
	v_readlane_b32 s1, v253, 44
	v_lshl_add_u32 v208, v156, 2, 0
	v_lshl_add_u64 v[164:165], s[0:1], 0, v[128:129]
	s_mov_b32 s0, 0xa300000
	s_cmp_eq_u64 s[30:31], 0
	v_readlane_b32 s19, v253, 37
	v_add_u32_e32 v158, s50, v156
	v_ashrrev_i32_e32 v159, 31, v158
	v_lshlrev_b64 v[246:247], 10, v[158:159]
	v_lshl_add_u64 v[246:247], v[246:247], 0, v[154:155]
	v_lshlrev_b64 v[246:247], 2, v[246:247]
	v_lshl_add_u64 v[246:247], s[90:91], 0, v[246:247]
	global_load_dwordx4 v[212:215], v[246:247], off
	global_load_dwordx4 v[216:219], v[246:247], off offset:64
	global_load_dwordx4 v[220:223], v[246:247], off offset:512
	global_load_dwordx4 v[224:227], v[246:247], off offset:576
	v_add_u32_e32 v156, 16, v158
	v_ashrrev_i32_e32 v157, 31, v156
	v_lshlrev_b64 v[246:247], 10, v[156:157]
	v_lshl_add_u64 v[246:247], v[246:247], 0, v[154:155]
	v_lshlrev_b64 v[246:247], 2, v[246:247]
	v_lshl_add_u64 v[246:247], s[90:91], 0, v[246:247]
	global_load_dwordx4 v[228:231], v[246:247], off
	global_load_dwordx4 v[232:235], v[246:247], off offset:64
	global_load_dwordx4 v[236:239], v[246:247], off offset:512
	global_load_dwordx4 v[240:243], v[246:247], off offset:576
	global_load_dwordx4 v[172:175], v[162:163], off
	global_load_dwordx4 v[180:183], v[164:165], off
	global_load_dwordx4 v[140:143], v[162:163], off offset:64
	global_load_dwordx4 v[184:187], v[164:165], off offset:64
	global_load_dwordx4 v[136:139], v[162:163], off offset:512
	global_load_dwordx4 v[244:247], v[164:165], off offset:512
	global_load_dwordx4 v[132:135], v[162:163], off offset:576
	global_load_dwordx4 v[166:169], v[164:165], off offset:576
	s_waitcnt lgkmcnt(0)
	s_barrier
	s_waitcnt vmcnt(0)
	v_pk_mul_f32 v[172:173], v[172:173], v[180:181]
	v_pk_mul_f32 v[174:175], v[174:175], v[182:183]
	v_pk_mul_f32 v[140:141], v[140:141], v[184:185]
	v_pk_mul_f32 v[142:143], v[142:143], v[186:187]
	v_pk_mul_f32 v[136:137], v[136:137], v[244:245]
	v_pk_mul_f32 v[138:139], v[138:139], v[246:247]
	v_pk_mul_f32 v[132:133], v[132:133], v[166:167]
	v_pk_mul_f32 v[134:135], v[134:135], v[168:169]
	ds_read_b32 v144, v208 offset:4096
	v_lshlrev_b64 v[180:181], 10, v[158:159]
	v_lshl_add_u64 v[180:181], v[180:181], 0, v[154:155]
	v_lshlrev_b64 v[180:181], 2, v[180:181]
	v_lshl_add_u64 v[182:183], s[88:89], 0, v[180:181]
	s_waitcnt lgkmcnt(0)
	v_fmamk_f32 v144, v144, 0x3a800000, v146
	v_cmp_gt_f32_e32 vcc, s67, v144
	v_mul_f32_e32 v244, 0x4b800000, v144
	s_nop 0
	v_cndmask_b32_e32 v144, v144, v244, vcc
	v_rsq_f32_e32 v144, v144
	s_nop 0
	v_mul_f32_e32 v244, 0x45800000, v144
	v_cndmask_b32_e32 v144, v144, v244, vcc
	v_mul_f32_e32 v144, v149, v144
	v_pk_mul_f32 v[184:185], v[172:173], v[144:145] op_sel_hi:[1,0]
	v_pk_mul_f32 v[186:187], v[174:175], v[144:145] op_sel_hi:[1,0]
	v_pk_fma_f32 v[88:89], v[88:89], v[184:185], v[212:213]
	v_pk_fma_f32 v[90:91], v[90:91], v[186:187], v[214:215]
	v_pk_mul_f32 v[184:185], v[140:141], v[144:145] op_sel_hi:[1,0]
	v_pk_mul_f32 v[186:187], v[142:143], v[144:145] op_sel_hi:[1,0]
	v_pk_fma_f32 v[104:105], v[104:105], v[184:185], v[216:217]
	v_pk_fma_f32 v[106:107], v[106:107], v[186:187], v[218:219]
	v_pk_mul_f32 v[184:185], v[136:137], v[144:145] op_sel_hi:[1,0]
	v_pk_mul_f32 v[186:187], v[138:139], v[144:145] op_sel_hi:[1,0]
	v_pk_fma_f32 v[100:101], v[100:101], v[184:185], v[220:221]
	v_pk_fma_f32 v[102:103], v[102:103], v[186:187], v[222:223]
	v_pk_mul_f32 v[184:185], v[132:133], v[144:145] op_sel_hi:[1,0]
	v_pk_mul_f32 v[186:187], v[134:135], v[144:145] op_sel_hi:[1,0]
	v_pk_fma_f32 v[84:85], v[84:85], v[184:185], v[224:225]
	v_pk_fma_f32 v[86:87], v[86:87], v[186:187], v[226:227]
	v_add_u32_e32 v160, 32, v158
	v_ashrrev_i32_e32 v161, 31, v160
	v_lshlrev_b64 v[246:247], 10, v[160:161]
	v_lshl_add_u64 v[246:247], v[246:247], 0, v[154:155]
	v_lshlrev_b64 v[246:247], 2, v[246:247]
	v_lshl_add_u64 v[246:247], s[90:91], 0, v[246:247]
	global_load_dwordx4 v[212:215], v[246:247], off
	global_load_dwordx4 v[216:219], v[246:247], off offset:64
	global_load_dwordx4 v[220:223], v[246:247], off offset:512
	global_load_dwordx4 v[224:227], v[246:247], off offset:576
	ds_read_b32 v144, v208 offset:4160
	v_lshlrev_b64 v[180:181], 10, v[156:157]
	v_lshl_add_u64 v[180:181], v[180:181], 0, v[154:155]
	v_lshlrev_b64 v[180:181], 2, v[180:181]
	v_lshl_add_u64 v[182:183], s[88:89], 0, v[180:181]
	s_waitcnt lgkmcnt(0)
;     __device__ __forceinline__ void fused(f32x4 (&acc)[2][2][4][2], const Unit& u, int wr, int wc, int fr, int fq, LAS unsigned char* lds, int wid, int lane) const {
;     ...
;                 for (int m = 0; m < 4; ++m) { const int r = ai * HALF + wr * 64 + m * 16 + fr; const float r1 = rsqrtf(S[r] * (1.0f / D) + EPS) * wgt; const size_t off = (size_t)(u.pm * BM + r) * D + col0;
; #pragma unroll
;                     for (int bj = 0; bj < 2; ++bj)
; #pragma unroll
;                         for (int n = 0; n < 2; ++n) { const f32x4 xv = *(const f32x4*)(xin + off + bj * HALF + n * 16); const f32x4 xn = xv + (cw[bj][n] * r1) * acc[ai][bj][m][n];
;                             acc[ai][bj][m][n] = xn; *(f32x4*)(xout + off + bj * HALF + n * 16) = xn; }
;                     asm volatile("" : "+v"(acc[ai][0][m][0]), "+v"(acc[ai][0][m][1]), "+v"(acc[ai][1][m][0]), "+v"(acc[ai][1][m][1]));
;                     asm volatile("" ::: "memory"); }
	v_fmamk_f32 v144, v144, 0x3a800000, v146
	v_cmp_gt_f32_e32 vcc, s67, v144
	v_mul_f32_e32 v244, 0x4b800000, v144
	s_nop 0
	v_cndmask_b32_e32 v144, v144, v244, vcc
	v_rsq_f32_e32 v144, v144
	s_nop 0
	v_mul_f32_e32 v244, 0x45800000, v144
	v_cndmask_b32_e32 v144, v144, v244, vcc
	v_mul_f32_e32 v144, v149, v144
	v_pk_mul_f32 v[184:185], v[172:173], v[144:145] op_sel_hi:[1,0]
	v_pk_mul_f32 v[186:187], v[174:175], v[144:145] op_sel_hi:[1,0]
	v_pk_fma_f32 v[76:77], v[76:77], v[184:185], v[228:229]
	v_pk_fma_f32 v[78:79], v[78:79], v[186:187], v[230:231]
	v_pk_mul_f32 v[184:185], v[140:141], v[144:145] op_sel_hi:[1,0]
	v_pk_mul_f32 v[186:187], v[142:143], v[144:145] op_sel_hi:[1,0]
	v_pk_fma_f32 v[92:93], v[92:93], v[184:185], v[232:233]
	v_pk_fma_f32 v[94:95], v[94:95], v[186:187], v[234:235]
	v_pk_mul_f32 v[184:185], v[136:137], v[144:145] op_sel_hi:[1,0]
	v_pk_mul_f32 v[186:187], v[138:139], v[144:145] op_sel_hi:[1,0]
	v_pk_fma_f32 v[80:81], v[80:81], v[184:185], v[236:237]
	v_pk_fma_f32 v[82:83], v[82:83], v[186:187], v[238:239]
	v_pk_mul_f32 v[184:185], v[132:133], v[144:145] op_sel_hi:[1,0]
	v_pk_mul_f32 v[186:187], v[134:135], v[144:145] op_sel_hi:[1,0]
	v_pk_fma_f32 v[72:73], v[72:73], v[184:185], v[240:241]
	v_pk_fma_f32 v[74:75], v[74:75], v[186:187], v[242:243]
	v_add_u32_e32 v162, 48, v158
	v_ashrrev_i32_e32 v163, 31, v162
	v_lshlrev_b64 v[246:247], 10, v[162:163]
	v_lshl_add_u64 v[246:247], v[246:247], 0, v[154:155]
	v_lshlrev_b64 v[246:247], 2, v[246:247]
	v_lshl_add_u64 v[246:247], s[90:91], 0, v[246:247]
	global_load_dwordx4 v[228:231], v[246:247], off
	global_load_dwordx4 v[232:235], v[246:247], off offset:64
	global_load_dwordx4 v[236:239], v[246:247], off offset:512
	global_load_dwordx4 v[240:243], v[246:247], off offset:576
	ds_read_b32 v144, v208 offset:4224
	v_lshlrev_b64 v[180:181], 10, v[160:161]
	v_lshl_add_u64 v[180:181], v[180:181], 0, v[154:155]
	v_lshlrev_b64 v[180:181], 2, v[180:181]
	v_lshl_add_u64 v[182:183], s[88:89], 0, v[180:181]
	s_waitcnt lgkmcnt(0)
	v_fmamk_f32 v144, v144, 0x3a800000, v146
	v_cmp_gt_f32_e32 vcc, s67, v144
	v_mul_f32_e32 v244, 0x4b800000, v144
	s_nop 0
	v_cndmask_b32_e32 v144, v144, v244, vcc
	v_rsq_f32_e32 v144, v144
	s_nop 0
	v_mul_f32_e32 v244, 0x45800000, v144
	v_cndmask_b32_e32 v144, v144, v244, vcc
	v_mul_f32_e32 v144, v149, v144
	s_waitcnt vmcnt(4)
	v_pk_mul_f32 v[184:185], v[172:173], v[144:145] op_sel_hi:[1,0]
	v_pk_mul_f32 v[186:187], v[174:175], v[144:145] op_sel_hi:[1,0]
	v_pk_fma_f32 v[108:109], v[108:109], v[184:185], v[212:213]
	v_pk_fma_f32 v[110:111], v[110:111], v[186:187], v[214:215]
	v_pk_mul_f32 v[184:185], v[140:141], v[144:145] op_sel_hi:[1,0]
	v_pk_mul_f32 v[186:187], v[142:143], v[144:145] op_sel_hi:[1,0]
	v_pk_fma_f32 v[124:125], v[124:125], v[184:185], v[216:217]
	v_pk_fma_f32 v[126:127], v[126:127], v[186:187], v[218:219]
	v_pk_mul_f32 v[184:185], v[136:137], v[144:145] op_sel_hi:[1,0]
	v_pk_mul_f32 v[186:187], v[138:139], v[144:145] op_sel_hi:[1,0]
	v_pk_fma_f32 v[120:121], v[120:121], v[184:185], v[220:221]
	v_pk_fma_f32 v[122:123], v[122:123], v[186:187], v[222:223]
	v_pk_mul_f32 v[184:185], v[132:133], v[144:145] op_sel_hi:[1,0]
	v_pk_mul_f32 v[186:187], v[134:135], v[144:145] op_sel_hi:[1,0]
	v_pk_fma_f32 v[116:117], v[116:117], v[184:185], v[224:225]
	v_pk_fma_f32 v[118:119], v[118:119], v[186:187], v[226:227]
	v_add_u32_e32 v164, 0x80, v158
	v_ashrrev_i32_e32 v165, 31, v164
	v_lshlrev_b64 v[246:247], 10, v[164:165]
	v_lshl_add_u64 v[246:247], v[246:247], 0, v[154:155]
	v_lshlrev_b64 v[246:247], 2, v[246:247]
	v_lshl_add_u64 v[246:247], s[90:91], 0, v[246:247]
	global_load_dwordx4 v[212:215], v[246:247], off
	global_load_dwordx4 v[216:219], v[246:247], off offset:64
	global_load_dwordx4 v[220:223], v[246:247], off offset:512
	global_load_dwordx4 v[224:227], v[246:247], off offset:576
	ds_read_b32 v144, v208 offset:4288
	v_lshlrev_b64 v[180:181], 10, v[162:163]
	v_lshl_add_u64 v[180:181], v[180:181], 0, v[154:155]
	v_lshlrev_b64 v[180:181], 2, v[180:181]
	v_lshl_add_u64 v[182:183], s[88:89], 0, v[180:181]
	s_waitcnt lgkmcnt(0)
	v_fmamk_f32 v144, v144, 0x3a800000, v146
	v_cmp_gt_f32_e32 vcc, s67, v144
	v_mul_f32_e32 v244, 0x4b800000, v144
	s_nop 0
	v_cndmask_b32_e32 v144, v144, v244, vcc
	v_rsq_f32_e32 v144, v144
	s_nop 0
	v_mul_f32_e32 v244, 0x45800000, v144
	v_cndmask_b32_e32 v144, v144, v244, vcc
	v_mul_f32_e32 v144, v149, v144
	s_waitcnt vmcnt(4)
	v_pk_mul_f32 v[184:185], v[172:173], v[144:145] op_sel_hi:[1,0]
	v_pk_mul_f32 v[186:187], v[174:175], v[144:145] op_sel_hi:[1,0]
	v_pk_fma_f32 v[112:113], v[112:113], v[184:185], v[228:229]
	v_pk_fma_f32 v[114:115], v[114:115], v[186:187], v[230:231]
	v_pk_mul_f32 v[184:185], v[140:141], v[144:145] op_sel_hi:[1,0]
	v_pk_mul_f32 v[186:187], v[142:143], v[144:145] op_sel_hi:[1,0]
	v_pk_fma_f32 v[96:97], v[96:97], v[184:185], v[232:233]
	v_pk_fma_f32 v[98:99], v[98:99], v[186:187], v[234:235]
	v_pk_mul_f32 v[184:185], v[136:137], v[144:145] op_sel_hi:[1,0]
	v_pk_mul_f32 v[186:187], v[138:139], v[144:145] op_sel_hi:[1,0]
	v_pk_fma_f32 v[68:69], v[68:69], v[184:185], v[236:237]
	v_pk_fma_f32 v[70:71], v[70:71], v[186:187], v[238:239]
	v_pk_mul_f32 v[184:185], v[132:133], v[144:145] op_sel_hi:[1,0]
	v_pk_mul_f32 v[186:187], v[134:135], v[144:145] op_sel_hi:[1,0]
	v_pk_fma_f32 v[64:65], v[64:65], v[184:185], v[240:241]
	v_pk_fma_f32 v[66:67], v[66:67], v[186:187], v[242:243]
	v_add_u32_e32 v166, 0x90, v158
	v_ashrrev_i32_e32 v167, 31, v166
	v_lshlrev_b64 v[246:247], 10, v[166:167]
	v_lshl_add_u64 v[246:247], v[246:247], 0, v[154:155]
	v_lshlrev_b64 v[246:247], 2, v[246:247]
	v_lshl_add_u64 v[246:247], s[90:91], 0, v[246:247]
	global_load_dwordx4 v[228:231], v[246:247], off
	global_load_dwordx4 v[232:235], v[246:247], off offset:64
	global_load_dwordx4 v[236:239], v[246:247], off offset:512
	global_load_dwordx4 v[240:243], v[246:247], off offset:576
	ds_read_b32 v144, v208 offset:4608
	v_lshlrev_b64 v[180:181], 10, v[164:165]
	v_lshl_add_u64 v[180:181], v[180:181], 0, v[154:155]
	v_lshlrev_b64 v[180:181], 2, v[180:181]
	v_lshl_add_u64 v[182:183], s[88:89], 0, v[180:181]
	s_waitcnt lgkmcnt(0)
;     __device__ __forceinline__ void fused(f32x4 (&acc)[2][2][4][2], const Unit& u, int wr, int wc, int fr, int fq, LAS unsigned char* lds, int wid, int lane) const {
;     ...
;                 for (int m = 0; m < 4; ++m) { const int r = ai * HALF + wr * 64 + m * 16 + fr; const float r1 = rsqrtf(S[r] * (1.0f / D) + EPS) * wgt; const size_t off = (size_t)(u.pm * BM + r) * D + col0;
; #pragma unroll
;                     for (int bj = 0; bj < 2; ++bj)
; #pragma unroll
;                         for (int n = 0; n < 2; ++n) { const f32x4 xv = *(const f32x4*)(xin + off + bj * HALF + n * 16); const f32x4 xn = xv + (cw[bj][n] * r1) * acc[ai][bj][m][n];
;                             acc[ai][bj][m][n] = xn; *(f32x4*)(xout + off + bj * HALF + n * 16) = xn; }
;                     asm volatile("" : "+v"(acc[ai][0][m][0]), "+v"(acc[ai][0][m][1]), "+v"(acc[ai][1][m][0]), "+v"(acc[ai][1][m][1]));
;                     asm volatile("" ::: "memory"); }
;         }
;         if (H == nullptr) return;
	v_fmamk_f32 v144, v144, 0x3a800000, v146
	v_cmp_gt_f32_e32 vcc, s67, v144
	v_mul_f32_e32 v244, 0x4b800000, v144
	s_nop 0
	v_cndmask_b32_e32 v144, v144, v244, vcc
	v_rsq_f32_e32 v144, v144
	s_nop 0
	v_mul_f32_e32 v244, 0x45800000, v144
	v_cndmask_b32_e32 v144, v144, v244, vcc
	v_mul_f32_e32 v144, v149, v144
	s_waitcnt vmcnt(4)
	v_pk_mul_f32 v[184:185], v[172:173], v[144:145] op_sel_hi:[1,0]
	v_pk_mul_f32 v[186:187], v[174:175], v[144:145] op_sel_hi:[1,0]
	v_pk_fma_f32 v[60:61], v[60:61], v[184:185], v[212:213]
	v_pk_fma_f32 v[62:63], v[62:63], v[186:187], v[214:215]
	v_pk_mul_f32 v[184:185], v[140:141], v[144:145] op_sel_hi:[1,0]
	v_pk_mul_f32 v[186:187], v[142:143], v[144:145] op_sel_hi:[1,0]
	v_pk_fma_f32 v[56:57], v[56:57], v[184:185], v[216:217]
	v_pk_fma_f32 v[58:59], v[58:59], v[186:187], v[218:219]
	v_pk_mul_f32 v[184:185], v[136:137], v[144:145] op_sel_hi:[1,0]
	v_pk_mul_f32 v[186:187], v[138:139], v[144:145] op_sel_hi:[1,0]
	v_pk_fma_f32 v[52:53], v[52:53], v[184:185], v[220:221]
	v_pk_fma_f32 v[54:55], v[54:55], v[186:187], v[222:223]
	v_pk_mul_f32 v[184:185], v[132:133], v[144:145] op_sel_hi:[1,0]
	v_pk_mul_f32 v[186:187], v[134:135], v[144:145] op_sel_hi:[1,0]
	v_pk_fma_f32 v[48:49], v[48:49], v[184:185], v[224:225]
	v_pk_fma_f32 v[50:51], v[50:51], v[186:187], v[226:227]
	v_add_u32_e32 v168, 0xa0, v158
	v_ashrrev_i32_e32 v169, 31, v168
	v_lshlrev_b64 v[246:247], 10, v[168:169]
	v_lshl_add_u64 v[246:247], v[246:247], 0, v[154:155]
	v_lshlrev_b64 v[246:247], 2, v[246:247]
	v_lshl_add_u64 v[246:247], s[90:91], 0, v[246:247]
	global_load_dwordx4 v[212:215], v[246:247], off
	global_load_dwordx4 v[216:219], v[246:247], off offset:64
	global_load_dwordx4 v[220:223], v[246:247], off offset:512
	global_load_dwordx4 v[224:227], v[246:247], off offset:576
	ds_read_b32 v144, v208 offset:4672
	v_lshlrev_b64 v[180:181], 10, v[166:167]
	v_lshl_add_u64 v[180:181], v[180:181], 0, v[154:155]
	v_lshlrev_b64 v[180:181], 2, v[180:181]
	v_lshl_add_u64 v[182:183], s[88:89], 0, v[180:181]
	s_waitcnt lgkmcnt(0)
	v_fmamk_f32 v144, v144, 0x3a800000, v146
	v_cmp_gt_f32_e32 vcc, s67, v144
	v_mul_f32_e32 v244, 0x4b800000, v144
	s_nop 0
	v_cndmask_b32_e32 v144, v144, v244, vcc
	v_rsq_f32_e32 v144, v144
	s_nop 0
	v_mul_f32_e32 v244, 0x45800000, v144
	v_cndmask_b32_e32 v144, v144, v244, vcc
	v_mul_f32_e32 v144, v149, v144
	s_waitcnt vmcnt(4)
	v_pk_mul_f32 v[184:185], v[172:173], v[144:145] op_sel_hi:[1,0]
	v_pk_mul_f32 v[186:187], v[174:175], v[144:145] op_sel_hi:[1,0]
	v_pk_fma_f32 v[44:45], v[44:45], v[184:185], v[228:229]
	v_pk_fma_f32 v[46:47], v[46:47], v[186:187], v[230:231]
	v_pk_mul_f32 v[184:185], v[140:141], v[144:145] op_sel_hi:[1,0]
	v_pk_mul_f32 v[186:187], v[142:143], v[144:145] op_sel_hi:[1,0]
	v_pk_fma_f32 v[40:41], v[40:41], v[184:185], v[232:233]
	v_pk_fma_f32 v[42:43], v[42:43], v[186:187], v[234:235]
	v_pk_mul_f32 v[184:185], v[136:137], v[144:145] op_sel_hi:[1,0]
	v_pk_mul_f32 v[186:187], v[138:139], v[144:145] op_sel_hi:[1,0]
	v_pk_fma_f32 v[36:37], v[36:37], v[184:185], v[236:237]
	v_pk_fma_f32 v[38:39], v[38:39], v[186:187], v[238:239]
	v_pk_mul_f32 v[184:185], v[132:133], v[144:145] op_sel_hi:[1,0]
	v_pk_mul_f32 v[186:187], v[134:135], v[144:145] op_sel_hi:[1,0]
	v_pk_fma_f32 v[32:33], v[32:33], v[184:185], v[240:241]
	v_pk_fma_f32 v[34:35], v[34:35], v[186:187], v[242:243]
	v_add_u32_e32 v170, 0xb0, v158
	v_ashrrev_i32_e32 v171, 31, v170
	v_lshlrev_b64 v[246:247], 10, v[170:171]
	v_lshl_add_u64 v[246:247], v[246:247], 0, v[154:155]
	v_lshlrev_b64 v[246:247], 2, v[246:247]
	v_lshl_add_u64 v[246:247], s[90:91], 0, v[246:247]
	global_load_dwordx4 v[228:231], v[246:247], off
	global_load_dwordx4 v[232:235], v[246:247], off offset:64
	global_load_dwordx4 v[236:239], v[246:247], off offset:512
	global_load_dwordx4 v[240:243], v[246:247], off offset:576
	ds_read_b32 v144, v208 offset:4736
	v_lshlrev_b64 v[180:181], 10, v[168:169]
	v_lshl_add_u64 v[180:181], v[180:181], 0, v[154:155]
	v_lshlrev_b64 v[180:181], 2, v[180:181]
	v_lshl_add_u64 v[182:183], s[88:89], 0, v[180:181]
	s_waitcnt lgkmcnt(0)
	v_fmamk_f32 v144, v144, 0x3a800000, v146
	v_cmp_gt_f32_e32 vcc, s67, v144
	v_mul_f32_e32 v244, 0x4b800000, v144
	s_nop 0
	v_cndmask_b32_e32 v144, v144, v244, vcc
	v_rsq_f32_e32 v144, v144
	s_nop 0
	v_mul_f32_e32 v244, 0x45800000, v144
	v_cndmask_b32_e32 v144, v144, v244, vcc
	v_mul_f32_e32 v144, v149, v144
	s_waitcnt vmcnt(4)
	v_pk_mul_f32 v[184:185], v[172:173], v[144:145] op_sel_hi:[1,0]
	v_pk_mul_f32 v[186:187], v[174:175], v[144:145] op_sel_hi:[1,0]
	v_pk_fma_f32 v[28:29], v[28:29], v[184:185], v[212:213]
	v_pk_fma_f32 v[30:31], v[30:31], v[186:187], v[214:215]
	v_pk_mul_f32 v[184:185], v[140:141], v[144:145] op_sel_hi:[1,0]
	v_pk_mul_f32 v[186:187], v[142:143], v[144:145] op_sel_hi:[1,0]
	v_pk_fma_f32 v[24:25], v[24:25], v[184:185], v[216:217]
	v_pk_fma_f32 v[26:27], v[26:27], v[186:187], v[218:219]
	v_pk_mul_f32 v[184:185], v[136:137], v[144:145] op_sel_hi:[1,0]
	v_pk_mul_f32 v[186:187], v[138:139], v[144:145] op_sel_hi:[1,0]
	v_pk_fma_f32 v[20:21], v[20:21], v[184:185], v[220:221]
	v_pk_fma_f32 v[22:23], v[22:23], v[186:187], v[222:223]
	v_pk_mul_f32 v[184:185], v[132:133], v[144:145] op_sel_hi:[1,0]
	v_pk_mul_f32 v[186:187], v[134:135], v[144:145] op_sel_hi:[1,0]
	v_pk_fma_f32 v[16:17], v[16:17], v[184:185], v[224:225]
	v_pk_fma_f32 v[18:19], v[18:19], v[186:187], v[226:227]
	ds_read_b32 v144, v208 offset:4800
	v_lshlrev_b64 v[180:181], 10, v[170:171]
	v_lshl_add_u64 v[180:181], v[180:181], 0, v[154:155]
	v_lshlrev_b64 v[180:181], 2, v[180:181]
	v_lshl_add_u64 v[182:183], s[88:89], 0, v[180:181]
	s_waitcnt lgkmcnt(0)
	v_fmamk_f32 v144, v144, 0x3a800000, v146
	v_cmp_gt_f32_e32 vcc, s67, v144
	v_mul_f32_e32 v244, 0x4b800000, v144
	s_nop 0
	v_cndmask_b32_e32 v144, v144, v244, vcc
	v_rsq_f32_e32 v144, v144
	s_nop 0
	v_mul_f32_e32 v244, 0x45800000, v144
	v_cndmask_b32_e32 v144, v144, v244, vcc
	v_mul_f32_e32 v144, v149, v144
	s_waitcnt vmcnt(0)
	v_pk_mul_f32 v[184:185], v[172:173], v[144:145] op_sel_hi:[1,0]
	v_pk_mul_f32 v[186:187], v[174:175], v[144:145] op_sel_hi:[1,0]
	v_pk_fma_f32 v[12:13], v[12:13], v[184:185], v[228:229]
	v_pk_fma_f32 v[14:15], v[14:15], v[186:187], v[230:231]
	v_pk_mul_f32 v[184:185], v[140:141], v[144:145] op_sel_hi:[1,0]
	v_pk_mul_f32 v[186:187], v[142:143], v[144:145] op_sel_hi:[1,0]
	v_pk_fma_f32 v[8:9], v[8:9], v[184:185], v[232:233]
	v_pk_fma_f32 v[10:11], v[10:11], v[186:187], v[234:235]
	v_pk_mul_f32 v[184:185], v[136:137], v[144:145] op_sel_hi:[1,0]
	v_pk_mul_f32 v[186:187], v[138:139], v[144:145] op_sel_hi:[1,0]
	v_pk_fma_f32 v[4:5], v[4:5], v[184:185], v[236:237]
	v_pk_fma_f32 v[6:7], v[6:7], v[186:187], v[238:239]
	v_pk_mul_f32 v[184:185], v[132:133], v[144:145] op_sel_hi:[1,0]
	v_pk_mul_f32 v[186:187], v[134:135], v[144:145] op_sel_hi:[1,0]
	v_pk_fma_f32 v[0:1], v[0:1], v[184:185], v[240:241]
	v_pk_fma_f32 v[2:3], v[2:3], v[186:187], v[242:243]
	s_nop 1
	s_cbranch_scc0 .Lxs_skip
; __device__ __forceinline__ void row_exchange(const f32x4 (&v)[2][2][4][2], const Unit& u, int wr, int wc, int fr, int fq, LAS unsigned char* lds, int wid, int lane, float* slots, unsigned* cnt) {
;     ...
;             float sq = 0.f;
; #pragma unroll
;             for (int bj = 0; bj < 2; ++bj)
; #pragma unroll
;                 for (int n = 0; n < 2; ++n) { const f32x4 x = v[ai][bj][m][n]; sq += (x[0] * x[0] + x[1] * x[1]) + (x[2] * x[2] + x[3] * x[3]); }
;             sq += __shfl_xor(sq, 16); sq += __shfl_xor(sq, 32);
;             if (fq == 0) P[(ai * HALF + wr * 64 + m * 16 + fr) * 4 + wc] = sq;
;     __device__ __forceinline__ void fused(f32x4 (&acc)[2][2][4][2], const Unit& u, int wr, int wc, int fr, int fq, LAS unsigned char* lds, int wid, int lane) const {
;     ...
;                             acc[ai][bj][m][n] = xn; *(f32x4*)(xout + off + bj * HALF + n * 16) = xn; }
;                     asm volatile("" : "+v"(acc[ai][0][m][0]), "+v"(acc[ai][0][m][1]), "+v"(acc[ai][1][m][0]), "+v"(acc[ai][1][m][1]));
;                     asm volatile("" ::: "memory"); }
;         }
;         if (H == nullptr) return;
	v_lshlrev_b64 v[244:245], 10, v[158:159]
	v_lshl_add_u64 v[244:245], v[244:245], 0, v[154:155]
	v_lshlrev_b64 v[244:245], 2, v[244:245]
	v_lshl_add_u64 v[246:247], s[88:89], 0, v[244:245]
	global_store_dwordx4 v[246:247], v[88:91], off
	global_store_dwordx4 v[246:247], v[104:107], off offset:64
	global_store_dwordx4 v[246:247], v[100:103], off offset:512
	global_store_dwordx4 v[246:247], v[84:87], off offset:576
	v_lshlrev_b64 v[244:245], 10, v[156:157]
	v_lshl_add_u64 v[244:245], v[244:245], 0, v[154:155]
	v_lshlrev_b64 v[244:245], 2, v[244:245]
	v_lshl_add_u64 v[246:247], s[88:89], 0, v[244:245]
	global_store_dwordx4 v[246:247], v[76:79], off
	global_store_dwordx4 v[246:247], v[92:95], off offset:64
	global_store_dwordx4 v[246:247], v[80:83], off offset:512
	global_store_dwordx4 v[246:247], v[72:75], off offset:576
	v_lshlrev_b64 v[244:245], 10, v[160:161]
	v_lshl_add_u64 v[244:245], v[244:245], 0, v[154:155]
	v_lshlrev_b64 v[244:245], 2, v[244:245]
	v_lshl_add_u64 v[246:247], s[88:89], 0, v[244:245]
	global_store_dwordx4 v[246:247], v[108:111], off
	global_store_dwordx4 v[246:247], v[124:127], off offset:64
	global_store_dwordx4 v[246:247], v[120:123], off offset:512
	global_store_dwordx4 v[246:247], v[116:119], off offset:576
	v_lshlrev_b64 v[244:245], 10, v[162:163]
	v_lshl_add_u64 v[244:245], v[244:245], 0, v[154:155]
	v_lshlrev_b64 v[244:245], 2, v[244:245]
	v_lshl_add_u64 v[246:247], s[88:89], 0, v[244:245]
	global_store_dwordx4 v[246:247], v[112:115], off
	global_store_dwordx4 v[246:247], v[96:99], off offset:64
	global_store_dwordx4 v[246:247], v[68:71], off offset:512
	global_store_dwordx4 v[246:247], v[64:67], off offset:576
	v_lshlrev_b64 v[244:245], 10, v[164:165]
	v_lshl_add_u64 v[244:245], v[244:245], 0, v[154:155]
	v_lshlrev_b64 v[244:245], 2, v[244:245]
	v_lshl_add_u64 v[246:247], s[88:89], 0, v[244:245]
	global_store_dwordx4 v[246:247], v[60:63], off
	global_store_dwordx4 v[246:247], v[56:59], off offset:64
	global_store_dwordx4 v[246:247], v[52:55], off offset:512
	global_store_dwordx4 v[246:247], v[48:51], off offset:576
	v_lshlrev_b64 v[244:245], 10, v[166:167]
	v_lshl_add_u64 v[244:245], v[244:245], 0, v[154:155]
	v_lshlrev_b64 v[244:245], 2, v[244:245]
	v_lshl_add_u64 v[246:247], s[88:89], 0, v[244:245]
	global_store_dwordx4 v[246:247], v[44:47], off
	global_store_dwordx4 v[246:247], v[40:43], off offset:64
	global_store_dwordx4 v[246:247], v[36:39], off offset:512
	global_store_dwordx4 v[246:247], v[32:35], off offset:576
	v_lshlrev_b64 v[244:245], 10, v[168:169]
	v_lshl_add_u64 v[244:245], v[244:245], 0, v[154:155]
	v_lshlrev_b64 v[244:245], 2, v[244:245]
	v_lshl_add_u64 v[246:247], s[88:89], 0, v[244:245]
	global_store_dwordx4 v[246:247], v[28:31], off
	global_store_dwordx4 v[246:247], v[24:27], off offset:64
	global_store_dwordx4 v[246:247], v[20:23], off offset:512
	global_store_dwordx4 v[246:247], v[16:19], off offset:576
	v_lshlrev_b64 v[244:245], 10, v[170:171]
	v_lshl_add_u64 v[244:245], v[244:245], 0, v[154:155]
	v_lshlrev_b64 v[244:245], 2, v[244:245]
	v_lshl_add_u64 v[246:247], s[88:89], 0, v[244:245]
	global_store_dwordx4 v[246:247], v[12:15], off
	global_store_dwordx4 v[246:247], v[8:11], off offset:64
	global_store_dwordx4 v[246:247], v[4:7], off offset:512
	global_store_dwordx4 v[246:247], v[0:3], off offset:576
.Lxs_skip:
	s_cbranch_scc1 .LBB0_1153
	v_mul_f32_e32 v132, v89, v89
	v_mul_f32_e32 v133, v91, v91
	v_fmac_f32_e32 v132, v88, v88
	v_fmac_f32_e32 v133, v90, v90
	v_add_f32_e32 v132, v132, v133
	v_mul_f32_e32 v133, v105, v105
	v_mul_f32_e32 v134, v107, v107
	v_fmac_f32_e32 v133, v104, v104
	v_fmac_f32_e32 v134, v106, v106
	v_add_f32_e32 v133, v133, v134
	v_add_f32_e32 v132, v132, v133
	v_mul_f32_e32 v133, v101, v101
	v_mul_f32_e32 v134, v103, v103
	v_fmac_f32_e32 v133, v100, v100
	v_fmac_f32_e32 v134, v102, v102
	v_add_f32_e32 v133, v133, v134
	v_add_f32_e32 v132, v133, v132
	v_mul_f32_e32 v133, v85, v85
	v_mul_f32_e32 v134, v87, v87
	v_fmac_f32_e32 v133, v84, v84
	v_fmac_f32_e32 v134, v86, v86
	v_add_f32_e32 v133, v133, v134
	v_add_f32_e32 v132, v133, v132
	ds_bpermute_b32 v133, v177, v132
	s_waitcnt lgkmcnt(0)
	v_add_f32_e32 v132, v132, v133
	ds_bpermute_b32 v133, v178, v132
	s_and_saveexec_b64 s[0:1], s[8:9]
	s_cbranch_execz .LBB0_1119
	s_lshl_b32 s15, s80, 10
	s_add_i32 s15, s52, s15
	s_waitcnt lgkmcnt(0)
	v_add_f32_e32 v132, v132, v133
	v_lshl_add_u32 v133, v176, 4, s15
	ds_write_b32 v133, v132

;     __device__ __forceinline__ void fused(f32x4 (&acc)[2][2][4][2], const Unit& u, int wr, int wc, int fr, int fq, LAS unsigned char* lds, int wid, int lane) const {
;     ...
;                             acc[ai][bj][m][n] = xn; *(f32x4*)(xout + off + bj * HALF + n * 16) = xn; }
;     ...
;             f32x4 gm[2][2], sh[2][2];
; #pragma unroll
;             for (int bj = 0; bj < 2; ++bj)
; #pragma unroll
;                 for (int n = 0; n < 2; ++n) { const int c = col0 + bj * HALF + n * 16; gm[bj][n] = *(const f32x4*)(gpre + c) * (*(const f32x4*)(scale + mb + c) + 1.0f); sh[bj][n] = *(const f32x4*)(shift + mb + c); }
; #pragma unroll
;             for (int ai = 0; ai < 2; ++ai)
; #pragma unroll
;                 for (int m = 0; m < 4; ++m) { const int r = ai * HALF + wr * 64 + m * 16 + fr; const float r2 = rsqrtf(S[r] * (1.0f / D) + EPS); const size_t off = (size_t)(u.pm * BM + r) * D + col0;
.LBB0_1152:
	s_or_b64 exec, exec, s[6:7]
	v_readlane_b32 s6, v253, 51
	s_add_i32 s80, s6, s14
	s_lshl_b64 s[0:1], s[80:81], 12
	s_add_u32 s4, s36, s0
	s_addc_u32 s5, s37, s1
	s_add_i32 s80, s6, s16
	s_lshl_b64 s[0:1], s[80:81], 12
	s_add_u32 s0, s34, s0
	s_addc_u32 s1, s35, s1
	s_add_u32 s0, s0, s94
	v_readlane_b32 s6, v253, 45
	s_addc_u32 s1, s1, s95
	v_readlane_b32 s7, v253, 46
	v_lshl_add_u64 v[134:135], s[0:1], 0, v[128:129]
	s_mov_b32 s0, 0xa300000
	v_lshl_add_u64 v[184:185], s[6:7], 0, v[128:129]
	s_mov_b64 s[6:7], 0xa300000
	v_lshl_add_u64 v[186:187], v[134:135], 0, s[6:7]
	v_add_co_u32_e32 v134, vcc, s0, v134
	s_nop 1
	v_addc_co_u32_e32 v135, vcc, 0, v135, vcc
	s_add_u32 s4, s4, s94
	s_addc_u32 s5, s5, s95
	v_lshl_add_u64 v[128:129], s[4:5], 0, v[128:129]
	v_lshl_add_u64 v[192:193], v[128:129], 0, s[6:7]
	v_add_co_u32_e32 v128, vcc, s0, v128
	v_lshlrev_b64 v[158:159], 11, v[158:159]
	s_nop 0
	v_addc_co_u32_e32 v129, vcc, 0, v129, vcc
	global_load_dwordx4 v[212:215], v[134:135], off
	global_load_dwordx4 v[228:231], v[184:185], off
	global_load_dwordx4 v[216:219], v[186:187], off offset:64
	global_load_dwordx4 v[232:235], v[184:185], off offset:64
	global_load_dwordx4 v[220:223], v[186:187], off offset:512
	global_load_dwordx4 v[236:239], v[184:185], off offset:512
	global_load_dwordx4 v[224:227], v[186:187], off offset:576
	global_load_dwordx4 v[240:243], v[184:185], off offset:576
	global_load_dwordx4 v[128:131], v[128:129], off
	global_load_dwordx4 v[132:135], v[192:193], off offset:64
	global_load_dwordx4 v[136:139], v[192:193], off offset:512
	global_load_dwordx4 v[140:143], v[192:193], off offset:576
	s_waitcnt lgkmcnt(0)
	s_barrier
	s_nop 0
	v_lshlrev_b64 v[244:245], 1, v[158:159]
	v_lshlrev_b64 v[246:247], 2, v[154:155]
	v_lshl_add_u64 v[244:245], v[244:245], 0, v[246:247]
	v_lshl_add_u64 v[246:247], s[88:89], 0, v[244:245]
	global_store_dwordx4 v[246:247], v[88:91], off
	global_store_dwordx4 v[246:247], v[104:107], off offset:64
	global_store_dwordx4 v[246:247], v[100:103], off offset:512
	global_store_dwordx4 v[246:247], v[84:87], off offset:576
	v_lshlrev_b64 v[244:245], 10, v[156:157]
	v_lshl_add_u64 v[244:245], v[244:245], 0, v[154:155]
	v_lshlrev_b64 v[244:245], 2, v[244:245]
	v_lshl_add_u64 v[246:247], s[88:89], 0, v[244:245]
	global_store_dwordx4 v[246:247], v[76:79], off
	global_store_dwordx4 v[246:247], v[92:95], off offset:64
	global_store_dwordx4 v[246:247], v[80:83], off offset:512
	global_store_dwordx4 v[246:247], v[72:75], off offset:576
	v_lshlrev_b64 v[244:245], 10, v[160:161]
	v_lshl_add_u64 v[244:245], v[244:245], 0, v[154:155]
	v_lshlrev_b64 v[244:245], 2, v[244:245]
	v_lshl_add_u64 v[246:247], s[88:89], 0, v[244:245]
	global_store_dwordx4 v[246:247], v[108:111], off
	global_store_dwordx4 v[246:247], v[124:127], off offset:64
	global_store_dwordx4 v[246:247], v[120:123], off offset:512
	global_store_dwordx4 v[246:247], v[116:119], off offset:576
	v_lshlrev_b64 v[244:245], 10, v[162:163]
	v_lshl_add_u64 v[244:245], v[244:245], 0, v[154:155]
	v_lshlrev_b64 v[244:245], 2, v[244:245]
	v_lshl_add_u64 v[246:247], s[88:89], 0, v[244:245]
	global_store_dwordx4 v[246:247], v[112:115], off
	global_store_dwordx4 v[246:247], v[96:99], off offset:64
	global_store_dwordx4 v[246:247], v[68:71], off offset:512
	global_store_dwordx4 v[246:247], v[64:67], off offset:576
	v_lshlrev_b64 v[244:245], 10, v[164:165]
	v_lshl_add_u64 v[244:245], v[244:245], 0, v[154:155]
	v_lshlrev_b64 v[244:245], 2, v[244:245]
	v_lshl_add_u64 v[246:247], s[88:89], 0, v[244:245]
	global_store_dwordx4 v[246:247], v[60:63], off
	global_store_dwordx4 v[246:247], v[56:59], off offset:64
	global_store_dwordx4 v[246:247], v[52:55], off offset:512
	global_store_dwordx4 v[246:247], v[48:51], off offset:576
	v_lshlrev_b64 v[244:245], 10, v[166:167]
	v_lshl_add_u64 v[244:245], v[244:245], 0, v[154:155]
	v_lshlrev_b64 v[244:245], 2, v[244:245]
	v_lshl_add_u64 v[246:247], s[88:89], 0, v[244:245]
	global_store_dwordx4 v[246:247], v[44:47], off
	global_store_dwordx4 v[246:247], v[40:43], off offset:64
	global_store_dwordx4 v[246:247], v[36:39], off offset:512
	global_store_dwordx4 v[246:247], v[32:35], off offset:576
	v_lshlrev_b64 v[244:245], 10, v[168:169]
	v_lshl_add_u64 v[244:245], v[244:245], 0, v[154:155]
	v_lshlrev_b64 v[244:245], 2, v[244:245]
	v_lshl_add_u64 v[246:247], s[88:89], 0, v[244:245]
	global_store_dwordx4 v[246:247], v[28:31], off
	global_store_dwordx4 v[246:247], v[24:27], off offset:64
	global_store_dwordx4 v[246:247], v[20:23], off offset:512
	global_store_dwordx4 v[246:247], v[16:19], off offset:576
	v_lshlrev_b64 v[244:245], 10, v[170:171]
	v_lshl_add_u64 v[244:245], v[244:245], 0, v[154:155]
	v_lshlrev_b64 v[244:245], 2, v[244:245]
	v_lshl_add_u64 v[246:247], s[88:89], 0, v[244:245]
	global_store_dwordx4 v[246:247], v[12:15], off
	global_store_dwordx4 v[246:247], v[8:11], off offset:64
	global_store_dwordx4 v[246:247], v[4:7], off offset:512
	global_store_dwordx4 v[246:247], v[0:3], off offset:576
	ds_read_b32 v144, v208 offset:4096
	s_waitcnt vmcnt(36)
	v_pk_add_f32 v[214:215], v[214:215], 1.0 op_sel_hi:[1,0]
	v_pk_add_f32 v[212:213], v[212:213], 1.0 op_sel_hi:[1,0]
	v_pk_mul_f32 v[172:173], v[230:231], v[214:215]
	v_pk_mul_f32 v[174:175], v[228:229], v[212:213]
	v_pk_add_f32 v[218:219], v[218:219], 1.0 op_sel_hi:[1,0]
	v_pk_add_f32 v[216:217], v[216:217], 1.0 op_sel_hi:[1,0]
	v_pk_mul_f32 v[176:177], v[234:235], v[218:219]
	v_pk_mul_f32 v[178:179], v[232:233], v[216:217]
	v_pk_add_f32 v[222:223], v[222:223], 1.0 op_sel_hi:[1,0]
	v_pk_add_f32 v[220:221], v[220:221], 1.0 op_sel_hi:[1,0]
	v_pk_mul_f32 v[180:181], v[238:239], v[222:223]
	v_pk_mul_f32 v[182:183], v[236:237], v[220:221]
	v_pk_add_f32 v[226:227], v[226:227], 1.0 op_sel_hi:[1,0]
	v_pk_add_f32 v[224:225], v[224:225], 1.0 op_sel_hi:[1,0]
	v_pk_mul_f32 v[184:185], v[242:243], v[226:227]
	v_pk_mul_f32 v[186:187], v[240:241], v[224:225]
	s_waitcnt lgkmcnt(0)
; __device__ __forceinline__ unsigned cvt_pk_bf16(float lo, float hi) { unsigned r; asm volatile("v_cvt_pk_bf16_f32 %0, %1, %2" : "=v"(r) : "v"(lo), "v"(hi)); return r; }
;     __device__ __forceinline__ void fused(f32x4 (&acc)[2][2][4][2], const Unit& u, int wr, int wc, int fr, int fq, LAS unsigned char* lds, int wid, int lane) const {
;     ...
;             for (int ai = 0; ai < 2; ++ai)
; #pragma unroll
;                 for (int m = 0; m < 4; ++m) { const int r = ai * HALF + wr * 64 + m * 16 + fr; const float r2 = rsqrtf(S[r] * (1.0f / D) + EPS); const size_t off = (size_t)(u.pm * BM + r) * D + col0;
; #pragma unroll
;                     for (int bj = 0; bj < 2; ++bj)
; #pragma unroll
;                         for (int n = 0; n < 2; ++n) { const f32x4 hv = (acc[ai][bj][m][n] * r2) * gm[bj][n] + sh[bj][n];
;                             uint2 w2; w2.x = cvt_pk_bf16(hv[0], hv[1]); w2.y = cvt_pk_bf16(hv[2], hv[3]); *(uint2*)(H + off + bj * HALF + n * 16) = w2; }
;                     asm volatile("" ::: "memory"); }
	v_fmamk_f32 v144, v144, 0x3a800000, v146
	v_cmp_gt_f32_e32 vcc, s67, v144
	s_nop 0
	s_waitcnt vmcnt(32)
	v_mul_f32_e32 v192, 0x4b800000, v144
	v_cndmask_b32_e32 v144, v144, v192, vcc
	v_rsq_f32_e32 v144, v144
	s_nop 0
	v_mul_f32_e32 v192, 0x45800000, v144
	v_cndmask_b32_e32 v144, v144, v192, vcc
	v_pk_mul_f32 v[88:89], v[88:89], v[144:145] op_sel_hi:[1,0]
	v_pk_mul_f32 v[90:91], v[90:91], v[144:145] op_sel_hi:[1,0]
	v_pk_fma_f32 v[88:89], v[174:175], v[88:89], v[128:129]
	v_pk_fma_f32 v[90:91], v[172:173], v[90:91], v[130:131]
	v_cvt_pk_bf16_f32 v192, v88, v89
	v_lshlrev_b64 v[88:89], 1, v[154:155]
	v_cvt_pk_bf16_f32 v193, v90, v91
	v_lshl_add_u64 v[90:91], s[30:31], 0, v[158:159]
	v_pk_mul_f32 v[104:105], v[104:105], v[144:145] op_sel_hi:[1,0]
	v_pk_mul_f32 v[100:101], v[100:101], v[144:145] op_sel_hi:[1,0]
	v_pk_mul_f32 v[84:85], v[84:85], v[144:145] op_sel_hi:[1,0]
	v_lshl_add_u64 v[90:91], v[90:91], 0, v[88:89]
	v_pk_mul_f32 v[106:107], v[106:107], v[144:145] op_sel_hi:[1,0]
	v_pk_fma_f32 v[104:105], v[178:179], v[104:105], v[132:133]
	v_pk_mul_f32 v[102:103], v[102:103], v[144:145] op_sel_hi:[1,0]
	v_pk_fma_f32 v[100:101], v[182:183], v[100:101], v[136:137]
	v_pk_mul_f32 v[86:87], v[86:87], v[144:145] op_sel_hi:[1,0]
	global_store_dwordx2 v[90:91], v[192:193], off
	v_pk_fma_f32 v[106:107], v[176:177], v[106:107], v[134:135]
	v_cvt_pk_bf16_f32 v104, v104, v105
	v_pk_fma_f32 v[102:103], v[180:181], v[102:103], v[138:139]
	v_cvt_pk_bf16_f32 v105, v106, v107
	global_store_dwordx2 v[90:91], v[104:105], off offset:32
	v_cvt_pk_bf16_f32 v100, v100, v101
	v_cvt_pk_bf16_f32 v101, v102, v103
	global_store_dwordx2 v[90:91], v[100:101], off offset:256
	s_waitcnt lgkmcnt(0)
	s_nop 0
	v_pk_fma_f32 v[84:85], v[186:187], v[84:85], v[140:141]
	v_pk_fma_f32 v[86:87], v[184:185], v[86:87], v[142:143]
	v_cvt_pk_bf16_f32 v84, v84, v85
	s_nop 0
	v_cvt_pk_bf16_f32 v85, v86, v87
	global_store_dwordx2 v[90:91], v[84:85], off offset:288
	ds_read_b32 v84, v208 offset:4160
	v_lshlrev_b64 v[86:87], 11, v[156:157]
	s_waitcnt lgkmcnt(0)
	v_fmamk_f32 v84, v84, 0x3a800000, v146
	v_cmp_gt_f32_e32 vcc, s67, v84
	v_mul_f32_e32 v85, 0x4b800000, v84
	s_nop 0
	v_cndmask_b32_e32 v84, v84, v85, vcc
	v_rsq_f32_e32 v84, v84
	s_nop 0
	v_mul_f32_e32 v85, 0x45800000, v84
	v_cndmask_b32_e32 v84, v84, v85, vcc
	v_pk_mul_f32 v[76:77], v[76:77], v[84:85] op_sel_hi:[1,0]
	v_pk_mul_f32 v[78:79], v[78:79], v[84:85] op_sel_hi:[1,0]
	v_pk_fma_f32 v[76:77], v[174:175], v[76:77], v[128:129]
	v_pk_fma_f32 v[78:79], v[172:173], v[78:79], v[130:131]
	v_cvt_pk_bf16_f32 v76, v76, v77
	v_pk_mul_f32 v[72:73], v[72:73], v[84:85] op_sel_hi:[1,0]
	v_cvt_pk_bf16_f32 v77, v78, v79
	v_lshl_add_u64 v[78:79], s[30:31], 0, v[86:87]
	v_lshl_add_u64 v[78:79], v[78:79], 0, v[88:89]
	global_store_dwordx2 v[78:79], v[76:77], off
	v_pk_mul_f32 v[76:77], v[92:93], v[84:85] op_sel_hi:[1,0]
	v_pk_mul_f32 v[86:87], v[94:95], v[84:85] op_sel_hi:[1,0]
	v_pk_fma_f32 v[76:77], v[178:179], v[76:77], v[132:133]
	v_pk_fma_f32 v[86:87], v[176:177], v[86:87], v[134:135]
	v_cvt_pk_bf16_f32 v76, v76, v77
	v_pk_mul_f32 v[74:75], v[74:75], v[84:85] op_sel_hi:[1,0]
	v_cvt_pk_bf16_f32 v77, v86, v87
	global_store_dwordx2 v[78:79], v[76:77], off offset:32
	v_pk_mul_f32 v[76:77], v[80:81], v[84:85] op_sel_hi:[1,0]
	v_pk_mul_f32 v[80:81], v[82:83], v[84:85] op_sel_hi:[1,0]
	v_pk_fma_f32 v[76:77], v[182:183], v[76:77], v[136:137]
	v_pk_fma_f32 v[72:73], v[186:187], v[72:73], v[140:141]
	v_pk_fma_f32 v[80:81], v[180:181], v[80:81], v[138:139]
	v_cvt_pk_bf16_f32 v76, v76, v77
	v_pk_fma_f32 v[74:75], v[184:185], v[74:75], v[142:143]
	v_cvt_pk_bf16_f32 v77, v80, v81
	global_store_dwordx2 v[78:79], v[76:77], off offset:256
	v_cvt_pk_bf16_f32 v72, v72, v73
	v_cvt_pk_bf16_f32 v73, v74, v75
	global_store_dwordx2 v[78:79], v[72:73], off offset:288
	ds_read_b32 v72, v208 offset:4224
	v_lshlrev_b64 v[74:75], 11, v[160:161]
	v_lshl_add_u64 v[74:75], s[30:31], 0, v[74:75]
	v_lshl_add_u64 v[74:75], v[74:75], 0, v[88:89]
	s_waitcnt lgkmcnt(0)
	v_fmamk_f32 v72, v72, 0x3a800000, v146
	v_cmp_gt_f32_e32 vcc, s67, v72
	v_mul_f32_e32 v73, 0x4b800000, v72
	s_nop 0
	v_cndmask_b32_e32 v72, v72, v73, vcc
	v_rsq_f32_e32 v72, v72
	s_nop 0
	v_mul_f32_e32 v73, 0x45800000, v72
	v_cndmask_b32_e32 v72, v72, v73, vcc
	v_pk_mul_f32 v[76:77], v[108:109], v[72:73] op_sel_hi:[1,0]
	v_pk_mul_f32 v[78:79], v[110:111], v[72:73] op_sel_hi:[1,0]
	v_pk_fma_f32 v[76:77], v[174:175], v[76:77], v[128:129]
	v_pk_fma_f32 v[78:79], v[172:173], v[78:79], v[130:131]
	v_cvt_pk_bf16_f32 v76, v76, v77
	s_nop 0
	v_cvt_pk_bf16_f32 v77, v78, v79
	global_store_dwordx2 v[74:75], v[76:77], off
	v_pk_mul_f32 v[76:77], v[124:125], v[72:73] op_sel_hi:[1,0]
	v_pk_mul_f32 v[78:79], v[126:127], v[72:73] op_sel_hi:[1,0]
	v_pk_fma_f32 v[76:77], v[178:179], v[76:77], v[132:133]
	v_pk_fma_f32 v[78:79], v[176:177], v[78:79], v[134:135]
	v_cvt_pk_bf16_f32 v76, v76, v77
	s_nop 0
	v_cvt_pk_bf16_f32 v77, v78, v79
	global_store_dwordx2 v[74:75], v[76:77], off offset:32
	v_pk_mul_f32 v[76:77], v[120:121], v[72:73] op_sel_hi:[1,0]
	v_pk_mul_f32 v[78:79], v[122:123], v[72:73] op_sel_hi:[1,0]
	v_pk_fma_f32 v[76:77], v[182:183], v[76:77], v[136:137]
	v_pk_fma_f32 v[78:79], v[180:181], v[78:79], v[138:139]
	v_cvt_pk_bf16_f32 v76, v76, v77
	s_nop 0
	v_cvt_pk_bf16_f32 v77, v78, v79
	global_store_dwordx2 v[74:75], v[76:77], off offset:256
	v_pk_mul_f32 v[76:77], v[116:117], v[72:73] op_sel_hi:[1,0]
	v_pk_mul_f32 v[72:73], v[118:119], v[72:73] op_sel_hi:[1,0]
	v_pk_fma_f32 v[76:77], v[186:187], v[76:77], v[140:141]
	v_pk_fma_f32 v[72:73], v[184:185], v[72:73], v[142:143]
	v_cvt_pk_bf16_f32 v76, v76, v77
	s_nop 0
	v_cvt_pk_bf16_f32 v77, v72, v73
	global_store_dwordx2 v[74:75], v[76:77], off offset:288
	ds_read_b32 v72, v208 offset:4288
	v_lshlrev_b64 v[74:75], 11, v[162:163]
	v_lshl_add_u64 v[74:75], s[30:31], 0, v[74:75]
	v_lshl_add_u64 v[74:75], v[74:75], 0, v[88:89]
	s_waitcnt lgkmcnt(0)
; __device__ __forceinline__ unsigned cvt_pk_bf16(float lo, float hi) { unsigned r; asm volatile("v_cvt_pk_bf16_f32 %0, %1, %2" : "=v"(r) : "v"(lo), "v"(hi)); return r; }
;     __device__ __forceinline__ void fused(f32x4 (&acc)[2][2][4][2], const Unit& u, int wr, int wc, int fr, int fq, LAS unsigned char* lds, int wid, int lane) const {
;     ...
;             for (int ai = 0; ai < 2; ++ai)
; #pragma unroll
;                 for (int m = 0; m < 4; ++m) { const int r = ai * HALF + wr * 64 + m * 16 + fr; const float r2 = rsqrtf(S[r] * (1.0f / D) + EPS); const size_t off = (size_t)(u.pm * BM + r) * D + col0;
; #pragma unroll
;                     for (int bj = 0; bj < 2; ++bj)
; #pragma unroll
;                         for (int n = 0; n < 2; ++n) { const f32x4 hv = (acc[ai][bj][m][n] * r2) * gm[bj][n] + sh[bj][n];
;                             uint2 w2; w2.x = cvt_pk_bf16(hv[0], hv[1]); w2.y = cvt_pk_bf16(hv[2], hv[3]); *(uint2*)(H + off + bj * HALF + n * 16) = w2; }
;                     asm volatile("" ::: "memory"); }
	v_fmamk_f32 v72, v72, 0x3a800000, v146
	v_cmp_gt_f32_e32 vcc, s67, v72
	v_mul_f32_e32 v73, 0x4b800000, v72
	s_nop 0
	v_cndmask_b32_e32 v72, v72, v73, vcc
	v_rsq_f32_e32 v72, v72
	s_nop 0
	v_mul_f32_e32 v73, 0x45800000, v72
	v_cndmask_b32_e32 v72, v72, v73, vcc
	v_pk_mul_f32 v[76:77], v[112:113], v[72:73] op_sel_hi:[1,0]
	v_pk_mul_f32 v[78:79], v[114:115], v[72:73] op_sel_hi:[1,0]
	v_pk_fma_f32 v[76:77], v[174:175], v[76:77], v[128:129]
	v_pk_fma_f32 v[78:79], v[172:173], v[78:79], v[130:131]
	v_cvt_pk_bf16_f32 v76, v76, v77
	v_pk_mul_f32 v[68:69], v[68:69], v[72:73] op_sel_hi:[1,0]
	v_cvt_pk_bf16_f32 v77, v78, v79
	global_store_dwordx2 v[74:75], v[76:77], off
	v_pk_mul_f32 v[76:77], v[96:97], v[72:73] op_sel_hi:[1,0]
	v_pk_mul_f32 v[64:65], v[64:65], v[72:73] op_sel_hi:[1,0]
	v_pk_mul_f32 v[78:79], v[98:99], v[72:73] op_sel_hi:[1,0]
	v_pk_fma_f32 v[76:77], v[178:179], v[76:77], v[132:133]
	v_pk_mul_f32 v[70:71], v[70:71], v[72:73] op_sel_hi:[1,0]
	v_pk_fma_f32 v[68:69], v[182:183], v[68:69], v[136:137]
	v_pk_mul_f32 v[66:67], v[66:67], v[72:73] op_sel_hi:[1,0]
	v_pk_fma_f32 v[64:65], v[186:187], v[64:65], v[140:141]
	v_pk_fma_f32 v[78:79], v[176:177], v[78:79], v[134:135]
	v_cvt_pk_bf16_f32 v76, v76, v77
	v_pk_fma_f32 v[70:71], v[180:181], v[70:71], v[138:139]
	v_cvt_pk_bf16_f32 v77, v78, v79
	global_store_dwordx2 v[74:75], v[76:77], off offset:32
	v_cvt_pk_bf16_f32 v68, v68, v69
	v_cvt_pk_bf16_f32 v69, v70, v71
	global_store_dwordx2 v[74:75], v[68:69], off offset:256
	v_pk_fma_f32 v[66:67], v[184:185], v[66:67], v[142:143]
	v_cvt_pk_bf16_f32 v64, v64, v65
	s_nop 0
	v_cvt_pk_bf16_f32 v65, v66, v67
	global_store_dwordx2 v[74:75], v[64:65], off offset:288
	ds_read_b32 v64, v208 offset:4608
	v_lshlrev_b64 v[66:67], 11, v[164:165]
	s_waitcnt lgkmcnt(0)
	v_fmamk_f32 v64, v64, 0x3a800000, v146
	v_cmp_gt_f32_e32 vcc, s67, v64
	v_mul_f32_e32 v65, 0x4b800000, v64
	s_nop 0
	v_cndmask_b32_e32 v64, v64, v65, vcc
	v_rsq_f32_e32 v64, v64
	s_nop 0
	v_mul_f32_e32 v65, 0x45800000, v64
	v_cndmask_b32_e32 v64, v64, v65, vcc
	v_pk_mul_f32 v[60:61], v[60:61], v[64:65] op_sel_hi:[1,0]
	v_pk_mul_f32 v[62:63], v[62:63], v[64:65] op_sel_hi:[1,0]
	v_pk_fma_f32 v[60:61], v[174:175], v[60:61], v[128:129]
	v_pk_fma_f32 v[62:63], v[172:173], v[62:63], v[130:131]
	v_cvt_pk_bf16_f32 v60, v60, v61
	v_pk_mul_f32 v[56:57], v[56:57], v[64:65] op_sel_hi:[1,0]
	v_cvt_pk_bf16_f32 v61, v62, v63
	v_lshl_add_u64 v[62:63], s[30:31], 0, v[66:67]
	v_pk_mul_f32 v[52:53], v[52:53], v[64:65] op_sel_hi:[1,0]
	v_pk_mul_f32 v[48:49], v[48:49], v[64:65] op_sel_hi:[1,0]
	v_lshl_add_u64 v[62:63], v[62:63], 0, v[88:89]
	v_pk_mul_f32 v[58:59], v[58:59], v[64:65] op_sel_hi:[1,0]
	v_pk_fma_f32 v[56:57], v[178:179], v[56:57], v[132:133]
	v_pk_mul_f32 v[54:55], v[54:55], v[64:65] op_sel_hi:[1,0]
	v_pk_fma_f32 v[52:53], v[182:183], v[52:53], v[136:137]
	v_pk_mul_f32 v[50:51], v[50:51], v[64:65] op_sel_hi:[1,0]
	v_pk_fma_f32 v[48:49], v[186:187], v[48:49], v[140:141]
	global_store_dwordx2 v[62:63], v[60:61], off
	v_pk_fma_f32 v[58:59], v[176:177], v[58:59], v[134:135]
	v_cvt_pk_bf16_f32 v56, v56, v57
	v_pk_fma_f32 v[54:55], v[180:181], v[54:55], v[138:139]
	v_cvt_pk_bf16_f32 v57, v58, v59
	global_store_dwordx2 v[62:63], v[56:57], off offset:32
	v_cvt_pk_bf16_f32 v52, v52, v53
	v_cvt_pk_bf16_f32 v53, v54, v55
	global_store_dwordx2 v[62:63], v[52:53], off offset:256
	v_pk_fma_f32 v[50:51], v[184:185], v[50:51], v[142:143]
	v_cvt_pk_bf16_f32 v48, v48, v49
	s_nop 0
	v_cvt_pk_bf16_f32 v49, v50, v51
	global_store_dwordx2 v[62:63], v[48:49], off offset:288
	ds_read_b32 v48, v208 offset:4672
	v_lshlrev_b64 v[50:51], 11, v[166:167]
	s_waitcnt lgkmcnt(0)
; __device__ __forceinline__ unsigned cvt_pk_bf16(float lo, float hi) { unsigned r; asm volatile("v_cvt_pk_bf16_f32 %0, %1, %2" : "=v"(r) : "v"(lo), "v"(hi)); return r; }
;     __device__ __forceinline__ void fused(f32x4 (&acc)[2][2][4][2], const Unit& u, int wr, int wc, int fr, int fq, LAS unsigned char* lds, int wid, int lane) const {
;     ...
;             for (int ai = 0; ai < 2; ++ai)
; #pragma unroll
;                 for (int m = 0; m < 4; ++m) { const int r = ai * HALF + wr * 64 + m * 16 + fr; const float r2 = rsqrtf(S[r] * (1.0f / D) + EPS); const size_t off = (size_t)(u.pm * BM + r) * D + col0;
; #pragma unroll
;                     for (int bj = 0; bj < 2; ++bj)
; #pragma unroll
;                         for (int n = 0; n < 2; ++n) { const f32x4 hv = (acc[ai][bj][m][n] * r2) * gm[bj][n] + sh[bj][n];
;                             uint2 w2; w2.x = cvt_pk_bf16(hv[0], hv[1]); w2.y = cvt_pk_bf16(hv[2], hv[3]); *(uint2*)(H + off + bj * HALF + n * 16) = w2; }
;                     asm volatile("" ::: "memory"); }
	v_fmamk_f32 v48, v48, 0x3a800000, v146
	v_cmp_gt_f32_e32 vcc, s67, v48
	v_mul_f32_e32 v49, 0x4b800000, v48
	s_nop 0
	v_cndmask_b32_e32 v48, v48, v49, vcc
	v_rsq_f32_e32 v48, v48
	s_nop 0
	v_mul_f32_e32 v49, 0x45800000, v48
	v_cndmask_b32_e32 v48, v48, v49, vcc
	v_pk_mul_f32 v[44:45], v[44:45], v[48:49] op_sel_hi:[1,0]
	v_pk_mul_f32 v[46:47], v[46:47], v[48:49] op_sel_hi:[1,0]
	v_pk_fma_f32 v[44:45], v[174:175], v[44:45], v[128:129]
	v_pk_fma_f32 v[46:47], v[172:173], v[46:47], v[130:131]
	v_cvt_pk_bf16_f32 v44, v44, v45
	v_pk_mul_f32 v[40:41], v[40:41], v[48:49] op_sel_hi:[1,0]
	v_cvt_pk_bf16_f32 v45, v46, v47
	v_lshl_add_u64 v[46:47], s[30:31], 0, v[50:51]
	v_pk_mul_f32 v[36:37], v[36:37], v[48:49] op_sel_hi:[1,0]
	v_pk_mul_f32 v[32:33], v[32:33], v[48:49] op_sel_hi:[1,0]
	v_lshl_add_u64 v[46:47], v[46:47], 0, v[88:89]
	v_pk_mul_f32 v[42:43], v[42:43], v[48:49] op_sel_hi:[1,0]
	v_pk_fma_f32 v[40:41], v[178:179], v[40:41], v[132:133]
	v_pk_mul_f32 v[38:39], v[38:39], v[48:49] op_sel_hi:[1,0]
	v_pk_fma_f32 v[36:37], v[182:183], v[36:37], v[136:137]
	v_pk_mul_f32 v[34:35], v[34:35], v[48:49] op_sel_hi:[1,0]
	v_pk_fma_f32 v[32:33], v[186:187], v[32:33], v[140:141]
	global_store_dwordx2 v[46:47], v[44:45], off
	v_pk_fma_f32 v[42:43], v[176:177], v[42:43], v[134:135]
	v_cvt_pk_bf16_f32 v40, v40, v41
	v_pk_fma_f32 v[38:39], v[180:181], v[38:39], v[138:139]
	v_cvt_pk_bf16_f32 v41, v42, v43
	global_store_dwordx2 v[46:47], v[40:41], off offset:32
	v_cvt_pk_bf16_f32 v36, v36, v37
	v_cvt_pk_bf16_f32 v37, v38, v39
	global_store_dwordx2 v[46:47], v[36:37], off offset:256
	v_pk_fma_f32 v[34:35], v[184:185], v[34:35], v[142:143]
	v_cvt_pk_bf16_f32 v32, v32, v33
	s_nop 0
	v_cvt_pk_bf16_f32 v33, v34, v35
	global_store_dwordx2 v[46:47], v[32:33], off offset:288
	ds_read_b32 v32, v208 offset:4736
	v_lshlrev_b64 v[34:35], 11, v[168:169]
	s_waitcnt lgkmcnt(0)
	v_fmamk_f32 v32, v32, 0x3a800000, v146
	v_cmp_gt_f32_e32 vcc, s67, v32
	v_mul_f32_e32 v33, 0x4b800000, v32
	s_nop 0
	v_cndmask_b32_e32 v32, v32, v33, vcc
	v_rsq_f32_e32 v32, v32
	s_nop 0
	v_mul_f32_e32 v33, 0x45800000, v32
	v_cndmask_b32_e32 v32, v32, v33, vcc
	v_pk_mul_f32 v[28:29], v[28:29], v[32:33] op_sel_hi:[1,0]
	v_pk_mul_f32 v[30:31], v[30:31], v[32:33] op_sel_hi:[1,0]
	v_pk_fma_f32 v[28:29], v[174:175], v[28:29], v[128:129]
	v_pk_fma_f32 v[30:31], v[172:173], v[30:31], v[130:131]
	v_cvt_pk_bf16_f32 v28, v28, v29
	v_pk_mul_f32 v[24:25], v[24:25], v[32:33] op_sel_hi:[1,0]
	v_cvt_pk_bf16_f32 v29, v30, v31
	v_lshl_add_u64 v[30:31], s[30:31], 0, v[34:35]
	v_pk_mul_f32 v[20:21], v[20:21], v[32:33] op_sel_hi:[1,0]
	v_pk_mul_f32 v[16:17], v[16:17], v[32:33] op_sel_hi:[1,0]
	v_lshl_add_u64 v[30:31], v[30:31], 0, v[88:89]
	v_pk_mul_f32 v[26:27], v[26:27], v[32:33] op_sel_hi:[1,0]
	v_pk_fma_f32 v[24:25], v[178:179], v[24:25], v[132:133]
	v_pk_mul_f32 v[22:23], v[22:23], v[32:33] op_sel_hi:[1,0]
	v_pk_fma_f32 v[20:21], v[182:183], v[20:21], v[136:137]
	v_pk_mul_f32 v[18:19], v[18:19], v[32:33] op_sel_hi:[1,0]
	v_pk_fma_f32 v[16:17], v[186:187], v[16:17], v[140:141]
	global_store_dwordx2 v[30:31], v[28:29], off
	v_pk_fma_f32 v[26:27], v[176:177], v[26:27], v[134:135]
	v_cvt_pk_bf16_f32 v24, v24, v25
	v_pk_fma_f32 v[22:23], v[180:181], v[22:23], v[138:139]
	v_cvt_pk_bf16_f32 v25, v26, v27
	global_store_dwordx2 v[30:31], v[24:25], off offset:32
	v_cvt_pk_bf16_f32 v20, v20, v21
	v_cvt_pk_bf16_f32 v21, v22, v23
	global_store_dwordx2 v[30:31], v[20:21], off offset:256
	v_pk_fma_f32 v[18:19], v[184:185], v[18:19], v[142:143]
	v_cvt_pk_bf16_f32 v16, v16, v17
	s_nop 0
	v_cvt_pk_bf16_f32 v17, v18, v19
	global_store_dwordx2 v[30:31], v[16:17], off offset:288
	ds_read_b32 v16, v208 offset:4800
	v_lshlrev_b64 v[18:19], 11, v[170:171]
	s_waitcnt lgkmcnt(0)
	v_fmamk_f32 v16, v16, 0x3a800000, v146
	v_cmp_gt_f32_e32 vcc, s67, v16
	v_mul_f32_e32 v17, 0x4b800000, v16
	s_nop 0
	v_cndmask_b32_e32 v16, v16, v17, vcc
	v_rsq_f32_e32 v16, v16
	s_nop 0
	v_mul_f32_e32 v17, 0x45800000, v16
	v_cndmask_b32_e32 v16, v16, v17, vcc
	v_pk_mul_f32 v[12:13], v[12:13], v[16:17] op_sel_hi:[1,0]
	v_pk_mul_f32 v[14:15], v[14:15], v[16:17] op_sel_hi:[1,0]
	v_pk_fma_f32 v[12:13], v[174:175], v[12:13], v[128:129]
	v_pk_fma_f32 v[14:15], v[172:173], v[14:15], v[130:131]
	v_cvt_pk_bf16_f32 v12, v12, v13
	v_pk_mul_f32 v[8:9], v[8:9], v[16:17] op_sel_hi:[1,0]
	v_cvt_pk_bf16_f32 v13, v14, v15
	v_lshl_add_u64 v[14:15], s[30:31], 0, v[18:19]
	v_pk_mul_f32 v[4:5], v[4:5], v[16:17] op_sel_hi:[1,0]
	v_pk_mul_f32 v[0:1], v[0:1], v[16:17] op_sel_hi:[1,0]
	v_lshl_add_u64 v[14:15], v[14:15], 0, v[88:89]
	v_pk_mul_f32 v[10:11], v[10:11], v[16:17] op_sel_hi:[1,0]
	v_pk_fma_f32 v[8:9], v[178:179], v[8:9], v[132:133]
	v_pk_mul_f32 v[6:7], v[6:7], v[16:17] op_sel_hi:[1,0]
	v_pk_fma_f32 v[4:5], v[182:183], v[4:5], v[136:137]
	v_pk_mul_f32 v[2:3], v[2:3], v[16:17] op_sel_hi:[1,0]
	v_pk_fma_f32 v[0:1], v[186:187], v[0:1], v[140:141]
	global_store_dwordx2 v[14:15], v[12:13], off
	v_pk_fma_f32 v[10:11], v[176:177], v[10:11], v[134:135]
	v_cvt_pk_bf16_f32 v8, v8, v9
	v_pk_fma_f32 v[6:7], v[180:181], v[6:7], v[138:139]
	v_cvt_pk_bf16_f32 v9, v10, v11
	global_store_dwordx2 v[14:15], v[8:9], off offset:32
	v_cvt_pk_bf16_f32 v4, v4, v5
	v_cvt_pk_bf16_f32 v5, v6, v7
	global_store_dwordx2 v[14:15], v[4:5], off offset:256
	v_pk_fma_f32 v[2:3], v[184:185], v[2:3], v[142:143]
	v_cvt_pk_bf16_f32 v0, v0, v1
	s_nop 0
	v_cvt_pk_bf16_f32 v1, v2, v3
	global_store_dwordx2 v[14:15], v[0:1], off offset:288
	s_waitcnt vmcnt(29)
